# dt fold (spread) + P6 K-row norm: all units' loads issued up front, bodies back to back
# baseline (speedup 1.0000x reference)
.LBB0_1714:
	v_ashrrev_i32_e32 v76, 2, v11
	v_ashrrev_i32_e32 v77, 31, v76
	v_lshlrev_b64 v[76:77], 11, v[76:77]
	v_lshl_add_u64 v[34:35], v[0:1], 0, v[76:77]
	global_load_dwordx4 v[14:17], v[34:35], off
	global_load_dwordx4 v[60:63], v[2:3], off offset:16
	global_load_dwordx4 v[64:67], v[2:3], off
	global_load_dwordx4 v[68:71], v[4:5], off offset:16
	global_load_dwordx4 v[72:75], v[4:5], off
	s_mov_b32 s98, 1
	s_add_i32 s89, s89, s86
	v_add_u32_e32 v11, s4, v11
	s_cmpk_lt_i32 s89, 0x280
	s_cbranch_scc0 .Lkx_go
	v_ashrrev_i32_e32 v76, 2, v11
	v_ashrrev_i32_e32 v77, 31, v76
	v_lshlrev_b64 v[76:77], 11, v[76:77]
	v_lshl_add_u64 v[48:49], v[0:1], 0, v[76:77]
	global_load_dwordx4 v[50:53], v[48:49], off
	s_mov_b32 s98, 2
	s_add_i32 s89, s89, s86
	v_add_u32_e32 v11, s4, v11
	s_cmpk_lt_i32 s89, 0x280
	s_cbranch_scc0 .Lkx_go
	v_ashrrev_i32_e32 v76, 2, v11
	v_ashrrev_i32_e32 v77, 31, v76
	v_lshlrev_b64 v[76:77], 11, v[76:77]
	v_lshl_add_u64 v[54:55], v[0:1], 0, v[76:77]
	global_load_dwordx4 v[56:59], v[54:55], off
	s_mov_b32 s98, 3
	s_add_i32 s89, s89, s86
	v_add_u32_e32 v11, s4, v11
	s_cmpk_lt_i32 s89, 0x280
.Lkx_go:
	s_waitcnt vmcnt(0)
	v_mov_b32_e32 v18, v60
	v_mov_b32_e32 v19, v61
	v_mov_b32_e32 v20, v62
	v_mov_b32_e32 v21, v63
	v_mov_b32_e32 v22, v64
	v_mov_b32_e32 v23, v65
	v_mov_b32_e32 v24, v66
	v_mov_b32_e32 v25, v67
	v_mov_b32_e32 v26, v68
	v_mov_b32_e32 v27, v69
	v_mov_b32_e32 v28, v70
	v_mov_b32_e32 v29, v71
	v_mov_b32_e32 v30, v72
	v_mov_b32_e32 v31, v73
	v_mov_b32_e32 v32, v74
	v_mov_b32_e32 v33, v75
	v_lshlrev_b32_e32 v40, 16, v14
	v_and_b32_e32 v41, 0xffff0000, v14
	v_lshlrev_b32_e32 v36, 16, v17
	v_and_b32_e32 v37, 0xffff0000, v17
	v_lshlrev_b32_e32 v38, 16, v16
	v_and_b32_e32 v39, 0xffff0000, v16
	v_lshlrev_b32_e32 v16, 16, v15
	v_and_b32_e32 v17, 0xffff0000, v15
	v_pk_mul_f32 v[46:47], v[40:41], v[40:41]
	v_pk_mul_f32 v[44:45], v[16:17], v[16:17]
	v_add_f32_e32 v46, v46, v47
	v_add_f32_e32 v44, v44, v46
	v_pk_mul_f32 v[42:43], v[38:39], v[38:39]
	v_add_f32_e32 v44, v45, v44
	v_add_f32_e32 v42, v42, v44
	v_pk_mul_f32 v[14:15], v[36:37], v[36:37]
	v_add_f32_e32 v42, v43, v42
	v_add_f32_e32 v14, v14, v42
	v_add_f32_e32 v14, v15, v14
	ds_bpermute_b32 v15, v6, v14
	s_waitcnt lgkmcnt(0)
	v_add_f32_e32 v14, v14, v15
	ds_bpermute_b32 v15, v7, v14
	s_waitcnt lgkmcnt(0)
	v_add_f32_e32 v14, v14, v15
	ds_bpermute_b32 v15, v8, v14
	s_waitcnt lgkmcnt(0)
	v_add_f32_e32 v14, v14, v15
	ds_bpermute_b32 v15, v9, v14
	s_waitcnt lgkmcnt(0)
	v_add_f32_e32 v14, v14, v15
	ds_bpermute_b32 v15, v10, v14
	s_waitcnt lgkmcnt(0)
	v_add_f32_e32 v14, v14, v15
	v_fmamk_f32 v14, v14, 0x3b800000, v12
	v_mul_f32_e32 v15, 0x4f800000, v14
	v_cmp_gt_f32_e32 vcc, s5, v14
	s_nop 1
	v_cndmask_b32_e32 v14, v14, v15, vcc
	v_sqrt_f32_e32 v15, v14
	s_nop 0
	v_add_u32_e32 v42, -1, v15
	v_add_u32_e32 v43, 1, v15
	v_fma_f32 v44, -v42, v15, v14
	v_fma_f32 v45, -v43, v15, v14
	v_cmp_ge_f32_e64 s[0:1], 0, v44
	s_nop 1
	v_cndmask_b32_e64 v15, v15, v42, s[0:1]
	v_cmp_lt_f32_e64 s[0:1], 0, v45
	s_nop 1
	v_cndmask_b32_e64 v15, v15, v43, s[0:1]
	v_mul_f32_e32 v42, 0x37800000, v15
	v_cndmask_b32_e32 v15, v15, v42, vcc
	v_cmp_class_f32_e32 vcc, v14, v13
	s_nop 1
	v_cndmask_b32_e32 v14, v15, v14, vcc
	v_div_scale_f32 v15, s[0:1], v14, v14, 1.0
	v_rcp_f32_e32 v43, v15
	v_div_scale_f32 v42, vcc, 1.0, v14, 1.0
	v_fma_f32 v44, -v15, v43, 1.0
	v_fmac_f32_e32 v43, v44, v43
	v_mul_f32_e32 v44, v42, v43
	v_fma_f32 v45, -v15, v44, v42
	v_fmac_f32_e32 v44, v45, v43
	v_fma_f32 v15, -v15, v44, v42
	v_div_fmas_f32 v15, v15, v43, v44
	v_div_fixup_f32 v14, v15, v14, 1.0
	v_pk_mul_f32 v[40:41], v[14:15], v[40:41] op_sel_hi:[0,1]
	v_pk_mul_f32 v[16:17], v[14:15], v[16:17] op_sel_hi:[0,1]
	v_pk_mul_f32 v[38:39], v[14:15], v[38:39] op_sel_hi:[0,1]
	v_pk_mul_f32 v[14:15], v[14:15], v[36:37] op_sel_hi:[0,1]
	v_pk_mul_f32 v[22:23], v[22:23], v[40:41]
	v_pk_mul_f32 v[16:17], v[24:25], v[16:17]
	v_pk_mul_f32 v[18:19], v[18:19], v[38:39]
	v_pk_mul_f32 v[14:15], v[20:21], v[14:15]
	v_pk_mul_f32 v[20:21], v[30:31], v[22:23]
	v_pk_mul_f32 v[16:17], v[32:33], v[16:17]
	v_pk_mul_f32 v[18:19], v[26:27], v[18:19]
	v_pk_mul_f32 v[22:23], v[28:29], v[14:15]
	v_cvt_pk_bf16_f32 v14, v20, v21
	v_cvt_pk_bf16_f32 v15, v16, v17
	v_cvt_pk_bf16_f32 v16, v18, v19
	v_cvt_pk_bf16_f32 v17, v22, v23
	global_store_dwordx4 v[34:35], v[14:17], off
	s_cmp_lt_u32 s98, 2
	s_cbranch_scc1 .Lkx_done
	v_mov_b32_e32 v14, v50
	v_mov_b32_e32 v15, v51
	v_mov_b32_e32 v16, v52
	v_mov_b32_e32 v17, v53
	v_mov_b32_e32 v34, v48
	v_mov_b32_e32 v35, v49
	v_mov_b32_e32 v18, v60
	v_mov_b32_e32 v19, v61
	v_mov_b32_e32 v20, v62
	v_mov_b32_e32 v21, v63
	v_mov_b32_e32 v22, v64
	v_mov_b32_e32 v23, v65
	v_mov_b32_e32 v24, v66
	v_mov_b32_e32 v25, v67
	v_mov_b32_e32 v26, v68
	v_mov_b32_e32 v27, v69
	v_mov_b32_e32 v28, v70
	v_mov_b32_e32 v29, v71
	v_mov_b32_e32 v30, v72
	v_mov_b32_e32 v31, v73
	v_mov_b32_e32 v32, v74
	v_mov_b32_e32 v33, v75
	v_lshlrev_b32_e32 v40, 16, v14
	v_and_b32_e32 v41, 0xffff0000, v14
	v_lshlrev_b32_e32 v36, 16, v17
	v_and_b32_e32 v37, 0xffff0000, v17
	v_lshlrev_b32_e32 v38, 16, v16
	v_and_b32_e32 v39, 0xffff0000, v16
	v_lshlrev_b32_e32 v16, 16, v15
	v_and_b32_e32 v17, 0xffff0000, v15
	v_pk_mul_f32 v[46:47], v[40:41], v[40:41]
	v_pk_mul_f32 v[44:45], v[16:17], v[16:17]
	v_add_f32_e32 v46, v46, v47
	v_add_f32_e32 v44, v44, v46
	v_pk_mul_f32 v[42:43], v[38:39], v[38:39]
	v_add_f32_e32 v44, v45, v44
	v_add_f32_e32 v42, v42, v44
	v_pk_mul_f32 v[14:15], v[36:37], v[36:37]
	v_add_f32_e32 v42, v43, v42
	v_add_f32_e32 v14, v14, v42
	v_add_f32_e32 v14, v15, v14
	ds_bpermute_b32 v15, v6, v14
	s_waitcnt lgkmcnt(0)
	v_add_f32_e32 v14, v14, v15
	ds_bpermute_b32 v15, v7, v14
	s_waitcnt lgkmcnt(0)
	v_add_f32_e32 v14, v14, v15
	ds_bpermute_b32 v15, v8, v14
	s_waitcnt lgkmcnt(0)
	v_add_f32_e32 v14, v14, v15
	ds_bpermute_b32 v15, v9, v14
	s_waitcnt lgkmcnt(0)
	v_add_f32_e32 v14, v14, v15
	ds_bpermute_b32 v15, v10, v14
	s_waitcnt lgkmcnt(0)
	v_add_f32_e32 v14, v14, v15
	v_fmamk_f32 v14, v14, 0x3b800000, v12
	v_mul_f32_e32 v15, 0x4f800000, v14
	v_cmp_gt_f32_e32 vcc, s5, v14
	s_nop 1
	v_cndmask_b32_e32 v14, v14, v15, vcc
	v_sqrt_f32_e32 v15, v14
	s_nop 0
	v_add_u32_e32 v42, -1, v15
	v_add_u32_e32 v43, 1, v15
	v_fma_f32 v44, -v42, v15, v14
	v_fma_f32 v45, -v43, v15, v14
	v_cmp_ge_f32_e64 s[0:1], 0, v44
	s_nop 1
	v_cndmask_b32_e64 v15, v15, v42, s[0:1]
	v_cmp_lt_f32_e64 s[0:1], 0, v45
	s_nop 1
	v_cndmask_b32_e64 v15, v15, v43, s[0:1]
	v_mul_f32_e32 v42, 0x37800000, v15
	v_cndmask_b32_e32 v15, v15, v42, vcc
	v_cmp_class_f32_e32 vcc, v14, v13
	s_nop 1
	v_cndmask_b32_e32 v14, v15, v14, vcc
	v_div_scale_f32 v15, s[0:1], v14, v14, 1.0
	v_rcp_f32_e32 v43, v15
	v_div_scale_f32 v42, vcc, 1.0, v14, 1.0
	v_fma_f32 v44, -v15, v43, 1.0
	v_fmac_f32_e32 v43, v44, v43
	v_mul_f32_e32 v44, v42, v43
	v_fma_f32 v45, -v15, v44, v42
	v_fmac_f32_e32 v44, v45, v43
	v_fma_f32 v15, -v15, v44, v42
	v_div_fmas_f32 v15, v15, v43, v44
	v_div_fixup_f32 v14, v15, v14, 1.0
	v_pk_mul_f32 v[40:41], v[14:15], v[40:41] op_sel_hi:[0,1]
	v_pk_mul_f32 v[16:17], v[14:15], v[16:17] op_sel_hi:[0,1]
	v_pk_mul_f32 v[38:39], v[14:15], v[38:39] op_sel_hi:[0,1]
	v_pk_mul_f32 v[14:15], v[14:15], v[36:37] op_sel_hi:[0,1]
	v_pk_mul_f32 v[22:23], v[22:23], v[40:41]
	v_pk_mul_f32 v[16:17], v[24:25], v[16:17]
	v_pk_mul_f32 v[18:19], v[18:19], v[38:39]
	v_pk_mul_f32 v[14:15], v[20:21], v[14:15]
	v_pk_mul_f32 v[20:21], v[30:31], v[22:23]
	v_pk_mul_f32 v[16:17], v[32:33], v[16:17]
	v_pk_mul_f32 v[18:19], v[26:27], v[18:19]
	v_pk_mul_f32 v[22:23], v[28:29], v[14:15]
	v_cvt_pk_bf16_f32 v14, v20, v21
	v_cvt_pk_bf16_f32 v15, v16, v17
	v_cvt_pk_bf16_f32 v16, v18, v19
	v_cvt_pk_bf16_f32 v17, v22, v23
	global_store_dwordx4 v[34:35], v[14:17], off
	s_cmp_lt_u32 s98, 3
	s_cbranch_scc1 .Lkx_done
	v_mov_b32_e32 v14, v56
	v_mov_b32_e32 v15, v57
	v_mov_b32_e32 v16, v58
	v_mov_b32_e32 v17, v59
	v_mov_b32_e32 v34, v54
	v_mov_b32_e32 v35, v55
	v_mov_b32_e32 v18, v60
	v_mov_b32_e32 v19, v61
	v_mov_b32_e32 v20, v62
	v_mov_b32_e32 v21, v63
	v_mov_b32_e32 v22, v64
	v_mov_b32_e32 v23, v65
	v_mov_b32_e32 v24, v66
	v_mov_b32_e32 v25, v67
	v_mov_b32_e32 v26, v68
	v_mov_b32_e32 v27, v69
	v_mov_b32_e32 v28, v70
	v_mov_b32_e32 v29, v71
	v_mov_b32_e32 v30, v72
	v_mov_b32_e32 v31, v73
	v_mov_b32_e32 v32, v74
	v_mov_b32_e32 v33, v75
	v_lshlrev_b32_e32 v40, 16, v14
	v_and_b32_e32 v41, 0xffff0000, v14
	v_lshlrev_b32_e32 v36, 16, v17
	v_and_b32_e32 v37, 0xffff0000, v17
	v_lshlrev_b32_e32 v38, 16, v16
	v_and_b32_e32 v39, 0xffff0000, v16
	v_lshlrev_b32_e32 v16, 16, v15
	v_and_b32_e32 v17, 0xffff0000, v15
	v_pk_mul_f32 v[46:47], v[40:41], v[40:41]
	v_pk_mul_f32 v[44:45], v[16:17], v[16:17]
	v_add_f32_e32 v46, v46, v47
	v_add_f32_e32 v44, v44, v46
	v_pk_mul_f32 v[42:43], v[38:39], v[38:39]
	v_add_f32_e32 v44, v45, v44
	v_add_f32_e32 v42, v42, v44
	v_pk_mul_f32 v[14:15], v[36:37], v[36:37]
	v_add_f32_e32 v42, v43, v42
	v_add_f32_e32 v14, v14, v42
	v_add_f32_e32 v14, v15, v14
	ds_bpermute_b32 v15, v6, v14
	s_waitcnt lgkmcnt(0)
	v_add_f32_e32 v14, v14, v15
	ds_bpermute_b32 v15, v7, v14
	s_waitcnt lgkmcnt(0)
	v_add_f32_e32 v14, v14, v15
	ds_bpermute_b32 v15, v8, v14
	s_waitcnt lgkmcnt(0)
	v_add_f32_e32 v14, v14, v15
	ds_bpermute_b32 v15, v9, v14
	s_waitcnt lgkmcnt(0)
	v_add_f32_e32 v14, v14, v15
	ds_bpermute_b32 v15, v10, v14
	s_waitcnt lgkmcnt(0)
	v_add_f32_e32 v14, v14, v15
	v_fmamk_f32 v14, v14, 0x3b800000, v12
	v_mul_f32_e32 v15, 0x4f800000, v14
	v_cmp_gt_f32_e32 vcc, s5, v14
	s_nop 1
	v_cndmask_b32_e32 v14, v14, v15, vcc
	v_sqrt_f32_e32 v15, v14
	s_nop 0
	v_add_u32_e32 v42, -1, v15
	v_add_u32_e32 v43, 1, v15
	v_fma_f32 v44, -v42, v15, v14
	v_fma_f32 v45, -v43, v15, v14
	v_cmp_ge_f32_e64 s[0:1], 0, v44
	s_nop 1
	v_cndmask_b32_e64 v15, v15, v42, s[0:1]
	v_cmp_lt_f32_e64 s[0:1], 0, v45
	s_nop 1
	v_cndmask_b32_e64 v15, v15, v43, s[0:1]
	v_mul_f32_e32 v42, 0x37800000, v15
	v_cndmask_b32_e32 v15, v15, v42, vcc
	v_cmp_class_f32_e32 vcc, v14, v13
	s_nop 1
	v_cndmask_b32_e32 v14, v15, v14, vcc
	v_div_scale_f32 v15, s[0:1], v14, v14, 1.0
	v_rcp_f32_e32 v43, v15
	v_div_scale_f32 v42, vcc, 1.0, v14, 1.0
	v_fma_f32 v44, -v15, v43, 1.0
	v_fmac_f32_e32 v43, v44, v43
	v_mul_f32_e32 v44, v42, v43
	v_fma_f32 v45, -v15, v44, v42
	v_fmac_f32_e32 v44, v45, v43
	v_fma_f32 v15, -v15, v44, v42
	v_div_fmas_f32 v15, v15, v43, v44
	v_div_fixup_f32 v14, v15, v14, 1.0
	v_pk_mul_f32 v[40:41], v[14:15], v[40:41] op_sel_hi:[0,1]
	v_pk_mul_f32 v[16:17], v[14:15], v[16:17] op_sel_hi:[0,1]
	v_pk_mul_f32 v[38:39], v[14:15], v[38:39] op_sel_hi:[0,1]
	v_pk_mul_f32 v[14:15], v[14:15], v[36:37] op_sel_hi:[0,1]
	v_pk_mul_f32 v[22:23], v[22:23], v[40:41]
	v_pk_mul_f32 v[16:17], v[24:25], v[16:17]
	v_pk_mul_f32 v[18:19], v[18:19], v[38:39]
	v_pk_mul_f32 v[14:15], v[20:21], v[14:15]
	v_pk_mul_f32 v[20:21], v[30:31], v[22:23]
	v_pk_mul_f32 v[16:17], v[32:33], v[16:17]
	v_pk_mul_f32 v[18:19], v[26:27], v[18:19]
	v_pk_mul_f32 v[22:23], v[28:29], v[14:15]
	v_cvt_pk_bf16_f32 v14, v20, v21
	v_cvt_pk_bf16_f32 v15, v16, v17
	v_cvt_pk_bf16_f32 v16, v18, v19
	v_cvt_pk_bf16_f32 v17, v22, v23
	global_store_dwordx4 v[34:35], v[14:17], off
.Lkx_done:
.LBB0_1715:
	v_readlane_b32 s4, v244, 47
	v_readlane_b32 s5, v244, 48
	s_cmp_gt_i32 s5, 7
	s_cselect_b64 s[0:1], -1, 0
	s_and_b64 s[2:3], s[2:3], s[0:1]
	s_andn2_b64 vcc, exec, s[2:3]
	v_readlane_b32 s6, v244, 49
	v_readlane_b32 s7, v244, 50
	s_cbranch_vccnz .LBB0_1769
	s_waitcnt vmcnt(0)
	s_waitcnt vmcnt(0)
	s_barrier
	s_mov_b64 s[2:3], exec
	v_readlane_b32 s4, v244, 13
	v_readlane_b32 s5, v244, 14
	s_and_b64 s[4:5], s[2:3], s[4:5]
	s_mov_b64 exec, s[4:5]
	s_cbranch_execz .LBB0_1768
	s_add_i32 s4, 0, 0x23fc0
	v_mov_b32_e32 v0, s4
	s_waitcnt vmcnt(0) expcnt(0) lgkmcnt(0)
	ds_read_b32 v2, v0
	s_add_i32 s4, 0, 0x23fc4
	v_mov_b32_e32 v0, s4
	ds_read_b32 v0, v0
	s_waitcnt lgkmcnt(1)
	v_cmp_ne_u32_e32 vcc, 0, v2
	s_cbranch_vccnz .LBB0_1732
	v_readlane_b32 s4, v244, 8
	v_readlane_b32 s5, v244, 9
	v_readlane_b32 s36, v244, 0
	s_load_dwordx2 s[8:9], s[4:5], 0x4
	v_readlane_b32 s42, v244, 6
	v_readlane_b32 s43, v244, 7
	s_add_u32 s4, s42, 0x1fd00200
	s_addc_u32 s5, s43, 0
	s_add_u32 s6, s42, 0x1fd00400
	s_addc_u32 s7, s43, 0
	s_waitcnt lgkmcnt(0)
	s_mul_i32 s33, s8, s86
	s_add_u32 s8, s42, 0x1fd00500
	s_mul_i32 s33, s33, s9
	s_addc_u32 s9, s43, 0
	s_add_u32 s10, s42, 0x1fd00600
	s_addc_u32 s11, s43, 0
	s_add_u32 s12, s42, 0x1fd00700
	s_addc_u32 s13, s43, 0
	s_add_u32 s14, s42, 0x1fd00800
	s_addc_u32 s15, s43, 0
	s_add_u32 s16, s42, 0x1fd00900
	s_addc_u32 s17, s43, 0
	s_add_u32 s18, s42, 0x1fd00a00
	s_addc_u32 s19, s43, 0
	s_add_u32 s20, s42, 0x1fd00b00
	s_addc_u32 s21, s43, 0
	s_add_u32 s22, s42, 0x1fd00c00
	s_addc_u32 s23, s43, 0
	s_add_u32 s24, s42, 0x1fd00d00
	s_addc_u32 s25, s43, 0
	s_add_u32 s26, s42, 0x1fd00e00
	s_addc_u32 s27, s43, 0
	s_add_u32 s28, s42, 0x1fd00f00
	s_addc_u32 s29, s43, 0
	s_add_u32 s30, s42, 0x1fd01000
	s_addc_u32 s31, s43, 0
	s_add_u32 s34, s42, 0x1fd01100
	s_addc_u32 s35, s43, 0
	v_readlane_b32 s37, v244, 1
	s_add_u32 s36, s42, 0x1fd01200
	v_readlane_b32 s38, v244, 2
	s_addc_u32 s37, s43, 0
	v_readlane_b32 s39, v244, 3
	s_add_u32 s38, s42, 0x1fd01300
	s_addc_u32 s39, s43, 0
	s_mov_b32 s46, 1
	v_mov_b32_e32 v16, 0
	v_readlane_b32 s40, v244, 4
	v_readlane_b32 s41, v244, 5
	s_branch .LBB0_1720
